# conv2d: UV rows prefetched one column step ahead into spare registers; the per-step wait moved from mid-step to end of step (vmcnt(4), stores left in flight); raw-row register rotations moved behind t
# speedup vs baseline: 1.0193x; 1.0038x over previous
.Lq_set:
	s_mov_b32 s84, 0x1600
	s_mov_b32 s85, 0
	s_mov_b32 s96, 1
	s_mul_i32 s94, s100, 0x1600
	v_mov_b32_e32 v166, s99
	v_mul_hi_i32 v0, v166, s39
	v_lshrrev_b32_e32 v1, 31, v0
	v_ashrrev_i32_e32 v0, 1, v0
	v_add_u32_e32 v104, v0, v1
	v_mul_lo_u32 v0, v104, 11
	v_sub_u32_e32 v0, v166, v0
	v_lshl_or_b32 v46, v0, 8, v167
	v_ashrrev_i32_e32 v47, 31, v46
	v_lshlrev_b64 v[36:37], 2, v[46:47]
	v_lshl_add_u64 v[32:33], s[12:13], 0, v[36:37]
	v_add_co_u32_e32 v4, vcc, s48, v32
	v_lshl_add_u64 v[36:37], s[14:15], 0, v[36:37]
	s_nop 0
	v_addc_co_u32_e32 v5, vcc, 0, v33, vcc
	v_add_co_u32_e32 v8, vcc, s49, v32
	flat_load_dwordx4 v[0:3], v[32:33]
	s_nop 0
	flat_load_dwordx4 v[4:7], v[4:5] offset:3072
	v_addc_co_u32_e32 v9, vcc, 0, v33, vcc
	v_add_co_u32_e32 v12, vcc, s50, v32
	v_lshlrev_b32_e32 v43, 1, v104
	s_nop 0
	v_addc_co_u32_e32 v13, vcc, 0, v33, vcc
	v_add_co_u32_e32 v16, vcc, s51, v32
	flat_load_dwordx4 v[8:11], v[8:9] offset:2048
	s_nop 0
	flat_load_dwordx4 v[12:15], v[12:13] offset:1024
	v_addc_co_u32_e32 v17, vcc, 0, v33, vcc
	v_add_co_u32_e32 v20, vcc, s52, v32
	v_lshlrev_b32_e32 v44, 5, v104
	s_nop 0
	v_addc_co_u32_e32 v21, vcc, 0, v33, vcc
	v_add_co_u32_e32 v24, vcc, s53, v32
	flat_load_dwordx4 v[16:19], v[16:17]
	s_nop 0
	flat_load_dwordx4 v[20:23], v[20:21] offset:3072
	v_addc_co_u32_e32 v25, vcc, 0, v33, vcc
	v_add_co_u32_e32 v28, vcc, s54, v32
	v_and_b32_e32 v60, 0x7c, v43
	s_nop 0
	v_addc_co_u32_e32 v29, vcc, 0, v33, vcc
	v_add_co_u32_e32 v32, vcc, s55, v32
	flat_load_dwordx4 v[24:27], v[24:25] offset:2048
	s_nop 0
	flat_load_dwordx4 v[28:31], v[28:29] offset:1024
	v_addc_co_u32_e32 v33, vcc, 0, v33, vcc
	flat_load_dwordx4 v[32:35], v[32:33]
	v_and_b32_e32 v168, 32, v44
	v_add_u32_e32 v168, s100, v168
	flat_load_dwordx4 v[36:39], v[36:37]
	v_ashrrev_i32_e32 v105, 6, v104
	v_add_u32_e32 v43, -1, v168
	v_add_u32_e32 v62, -1, v60
	v_mad_i64_i32 v[44:45], s[4:5], v105, s57, v[40:41]
	v_cmp_gt_u32_e64 s[10:11], 64, v43
	v_cmp_gt_u32_e64 s[6:7], s58, v62
	v_lshl_add_u64 v[44:45], v[46:47], 1, v[44:45]
	s_and_b64 s[4:5], s[10:11], s[6:7]
	v_mov_b32_e32 v48, v42
	v_mov_b32_e32 v49, v42
	s_and_saveexec_b64 s[8:9], s[4:5]
	s_cbranch_execz .LBB0_934
	v_lshl_or_b32 v48, v62, 6, v43
	v_mul_i32_i24_e32 v48, 0x1600, v48
	v_mov_b32_e32 v49, v42
	v_lshl_add_u64 v[48:49], v[44:45], 0, v[48:49]
	flat_load_dwordx2 v[48:49], v[48:49]

.LBB0_949:
	s_or_b64 exec, exec, s[10:11]
	v_add_co_u32_e32 v86, vcc, s63, v128
	v_pk_mul_f32 v[94:95], v[6:7], v[76:77]
	s_nop 0
	v_addc_co_u32_e32 v87, vcc, 0, v129, vcc
	v_lshl_add_u64 v[178:179], v[116:117], 0, s[90:91]
	v_lshl_add_u64 v[180:181], v[110:111], 0, s[90:91]
	v_lshl_add_u64 v[182:183], v[100:101], 0, s[90:91]
	v_mov_b64_e32 v[88:89], v[190:191]
	v_mov_b64_e32 v[184:185], v[192:193]
	v_mov_b64_e32 v[186:187], v[194:195]
	v_mov_b64_e32 v[188:189], v[198:199]
	v_lshl_add_u64 v[200:201], v[86:87], 0, s[84:85]
	v_lshl_add_u64 v[202:203], v[178:179], 0, s[84:85]
	v_lshl_add_u64 v[204:205], v[180:181], 0, s[84:85]
	v_lshl_add_u64 v[206:207], v[182:183], 0, s[84:85]
	global_load_dwordx2 v[190:191], v[200:201], off offset:2560
	global_load_dwordx2 v[192:193], v[202:203], off offset:2560
	global_load_dwordx2 v[194:195], v[204:205], off offset:2560
	global_load_dwordx2 v[198:199], v[206:207], off offset:2560
	v_pk_mul_f32 v[96:97], v[4:5], v[72:73]
	v_lshlrev_b32_e32 v62, 16, v148
	v_and_b32_e32 v63, 0xffff0000, v148
	v_lshlrev_b32_e32 v64, 16, v149
	v_and_b32_e32 v65, 0xffff0000, v149
	v_pk_mul_f32 v[106:107], v[18:19], v[80:81]
	v_pk_mul_f32 v[108:109], v[16:17], v[78:79]
	v_pk_fma_f32 v[94:95], v[2:3], v[144:145], v[94:95]
	v_pk_fma_f32 v[96:97], v[0:1], v[142:143], v[96:97]
	v_lshlrev_b32_e32 v66, 16, v152
	v_and_b32_e32 v67, 0xffff0000, v152
	v_lshlrev_b32_e32 v68, 16, v153
	v_and_b32_e32 v69, 0xffff0000, v153
	v_lshlrev_b32_e32 v70, 16, v150
	v_and_b32_e32 v71, 0xffff0000, v150
	v_lshlrev_b32_e32 v74, 16, v151
	v_and_b32_e32 v75, 0xffff0000, v151
	v_pk_mul_f32 v[148:149], v[30:31], v[84:85]
	v_pk_mul_f32 v[150:151], v[28:29], v[82:83]
	v_pk_fma_f32 v[106:107], v[14:15], v[136:137], v[106:107]
	v_pk_fma_f32 v[108:109], v[12:13], v[134:135], v[108:109]
	v_pk_fma_f32 v[94:95], v[10:11], v[64:65], v[94:95]
	v_pk_fma_f32 v[96:97], v[8:9], v[62:63], v[96:97]
	v_pk_fma_f32 v[142:143], v[26:27], v[126:127], v[148:149]
	v_pk_fma_f32 v[144:145], v[24:25], v[122:123], v[150:151]
	v_pk_fma_f32 v[106:107], v[22:23], v[68:69], v[106:107]
	v_pk_fma_f32 v[108:109], v[20:21], v[66:67], v[108:109]
	v_pk_add_f32 v[94:95], v[38:39], v[94:95]
	v_pk_add_f32 v[96:97], v[36:37], v[96:97]
	v_pk_fma_f32 v[142:143], v[34:35], v[74:75], v[142:143]
	v_pk_fma_f32 v[144:145], v[32:33], v[70:71], v[144:145]
	v_pk_add_f32 v[94:95], v[106:107], v[94:95]
	v_pk_add_f32 v[96:97], v[108:109], v[96:97]
	v_pk_add_f32 v[94:95], v[142:143], v[94:95]
	v_pk_add_f32 v[96:97], v[144:145], v[96:97]
	v_mov_b64_e32 v[128:129], s[28:29]
	v_pk_mul_f32 v[106:107], v[94:95], v[94:95]
	v_pk_mul_f32 v[108:109], v[96:97], v[96:97]
	v_pk_fma_f32 v[106:107], v[106:107], s[26:27], v[128:129] op_sel_hi:[1,0,0] neg_lo:[1,0,0] neg_hi:[1,0,0]
	v_pk_fma_f32 v[108:109], v[108:109], s[26:27], v[128:129] op_sel_hi:[1,0,0] neg_lo:[1,0,0] neg_hi:[1,0,0]
	v_pk_mul_f32 v[106:107], v[94:95], v[106:107]
	v_pk_mul_f32 v[108:109], v[96:97], v[108:109]
	v_exp_f32_e32 v106, v106
	v_exp_f32_e32 v108, v108
	v_exp_f32_e32 v109, v109
	v_exp_f32_e32 v107, v107
	v_add_co_u32_e32 v116, vcc, s63, v116
	v_pk_add_f32 v[108:109], v[108:109], 1.0 op_sel_hi:[1,0]
	v_pk_add_f32 v[106:107], v[106:107], 1.0 op_sel_hi:[1,0]
	v_rcp_f32_e32 v108, v108
	v_rcp_f32_e32 v109, v109
	v_rcp_f32_e32 v106, v106
	v_rcp_f32_e32 v107, v107
	v_addc_co_u32_e32 v117, vcc, 0, v117, vcc
	v_pk_mul_f32 v[96:97], v[96:97], v[108:109]
	v_pk_mul_f32 v[94:95], v[94:95], v[106:107]
	v_pk_mul_f32 v[108:109], v[18:19], v[84:85]
	v_pk_mul_f32 v[142:143], v[16:17], v[82:83]
	v_pk_mul_f32 v[144:145], v[30:31], v[92:93]
	v_pk_fma_f32 v[108:109], v[14:15], v[126:127], v[108:109]
	v_add_co_u32_e32 v110, vcc, s63, v110
	v_pk_fma_f32 v[108:109], v[22:23], v[74:75], v[108:109]
	s_nop 0
	v_addc_co_u32_e32 v111, vcc, 0, v111, vcc
	v_add_co_u32_e32 v100, vcc, s63, v100
	s_nop 0
	v_addc_co_u32_e32 v101, vcc, 0, v101, vcc
	v_lshlrev_b32_e32 v43, 16, v88
	v_and_b32_e32 v88, 0xffff0000, v88
	v_lshlrev_b32_e32 v106, 16, v89
	v_and_b32_e32 v89, 0xffff0000, v89
	v_mul_f32_e32 v88, v97, v88
	v_mul_f32_e32 v89, v95, v89
	v_mul_f32_e32 v43, v96, v43
	v_mul_f32_e32 v94, v94, v106
	v_cvt_pk_bf16_f32 v88, v43, v88
	v_cvt_pk_bf16_f32 v89, v94, v89
	flat_store_dwordx2 v[86:87], v[88:89] offset:2560
	s_nop 1
	v_mov_b64_e32 v[94:95], v[184:185]
	v_pk_mul_f32 v[96:97], v[6:7], v[80:81]
	v_pk_mul_f32 v[106:107], v[4:5], v[78:79]
	v_pk_fma_f32 v[96:97], v[2:3], v[136:137], v[96:97]
	v_pk_fma_f32 v[106:107], v[0:1], v[134:135], v[106:107]
	v_lshlrev_b32_e32 v86, 16, v146
	v_and_b32_e32 v87, 0xffff0000, v146
	v_lshlrev_b32_e32 v88, 16, v147
	v_and_b32_e32 v89, 0xffff0000, v147
	v_pk_mul_f32 v[146:147], v[28:29], v[90:91]
	v_pk_fma_f32 v[134:135], v[12:13], v[122:123], v[142:143]
	v_pk_fma_f32 v[96:97], v[10:11], v[68:69], v[96:97]
	v_pk_fma_f32 v[106:107], v[8:9], v[66:67], v[106:107]
	v_pk_fma_f32 v[136:137], v[26:27], v[120:121], v[144:145]
	v_pk_fma_f32 v[142:143], v[24:25], v[118:119], v[146:147]
	v_pk_fma_f32 v[134:135], v[20:21], v[70:71], v[134:135]
	v_pk_add_f32 v[96:97], v[38:39], v[96:97]
	v_pk_add_f32 v[106:107], v[36:37], v[106:107]
	v_pk_fma_f32 v[136:137], v[34:35], v[88:89], v[136:137]
	v_pk_fma_f32 v[142:143], v[32:33], v[86:87], v[142:143]
	v_pk_add_f32 v[96:97], v[108:109], v[96:97]
	v_pk_add_f32 v[106:107], v[134:135], v[106:107]
	v_pk_add_f32 v[96:97], v[136:137], v[96:97]
	v_pk_add_f32 v[106:107], v[142:143], v[106:107]
	v_pk_mul_f32 v[108:109], v[96:97], v[96:97]
	v_pk_mul_f32 v[134:135], v[106:107], v[106:107]
	v_pk_fma_f32 v[108:109], v[108:109], s[26:27], v[128:129] op_sel_hi:[1,0,0] neg_lo:[1,0,0] neg_hi:[1,0,0]
	v_pk_fma_f32 v[134:135], v[134:135], s[26:27], v[128:129] op_sel_hi:[1,0,0] neg_lo:[1,0,0] neg_hi:[1,0,0]
	v_pk_mul_f32 v[108:109], v[96:97], v[108:109]
	v_pk_mul_f32 v[134:135], v[106:107], v[134:135]
	v_exp_f32_e32 v108, v108
	v_exp_f32_e32 v134, v134
	v_exp_f32_e32 v135, v135
	v_exp_f32_e32 v109, v109
	v_pk_mul_f32 v[136:137], v[30:31], v[102:103]
	v_pk_mul_f32 v[142:143], v[28:29], v[98:99]
	v_pk_add_f32 v[134:135], v[134:135], 1.0 op_sel_hi:[1,0]
	v_pk_add_f32 v[108:109], v[108:109], 1.0 op_sel_hi:[1,0]
	v_rcp_f32_e32 v134, v134
	v_rcp_f32_e32 v135, v135
	v_rcp_f32_e32 v108, v108
	v_rcp_f32_e32 v109, v109
	v_pk_mul_f32 v[106:107], v[106:107], v[134:135]
	v_pk_mul_f32 v[134:135], v[16:17], v[90:91]
	v_pk_mul_f32 v[96:97], v[96:97], v[108:109]
	s_nop 0
	v_lshlrev_b32_e32 v43, 16, v94
	v_and_b32_e32 v94, 0xffff0000, v94
	v_lshlrev_b32_e32 v108, 16, v95
	v_and_b32_e32 v95, 0xffff0000, v95
	v_mul_f32_e32 v94, v107, v94
	v_mul_f32_e32 v95, v97, v95
	v_mul_f32_e32 v43, v106, v43
	v_mul_f32_e32 v96, v96, v108
	v_cvt_pk_bf16_f32 v94, v43, v94
	v_cvt_pk_bf16_f32 v95, v96, v95
	flat_store_dwordx2 v[116:117], v[94:95] offset:2560
	s_nop 1
	v_mov_b64_e32 v[106:107], v[186:187]
	v_pk_mul_f32 v[108:109], v[6:7], v[84:85]
	v_pk_mul_f32 v[116:117], v[4:5], v[82:83]
	v_lshlrev_b32_e32 v94, 16, v124
	v_and_b32_e32 v95, 0xffff0000, v124
	v_lshlrev_b32_e32 v96, 16, v125
	v_and_b32_e32 v97, 0xffff0000, v125
	v_pk_mul_f32 v[124:125], v[18:19], v[92:93]
	v_pk_fma_f32 v[108:109], v[2:3], v[126:127], v[108:109]
	v_pk_fma_f32 v[116:117], v[0:1], v[122:123], v[116:117]
	v_pk_fma_f32 v[122:123], v[14:15], v[120:121], v[124:125]
	v_pk_fma_f32 v[124:125], v[12:13], v[118:119], v[134:135]
	v_pk_fma_f32 v[108:109], v[10:11], v[74:75], v[108:109]
	v_pk_fma_f32 v[116:117], v[8:9], v[70:71], v[116:117]
	v_pk_fma_f32 v[126:127], v[26:27], v[132:133], v[136:137]
	v_pk_fma_f32 v[134:135], v[24:25], v[130:131], v[142:143]
	v_pk_fma_f32 v[122:123], v[22:23], v[88:89], v[122:123]
	v_pk_fma_f32 v[124:125], v[20:21], v[86:87], v[124:125]
	v_pk_add_f32 v[108:109], v[38:39], v[108:109]
	v_pk_add_f32 v[116:117], v[36:37], v[116:117]
	v_pk_fma_f32 v[126:127], v[34:35], v[96:97], v[126:127]
	v_pk_fma_f32 v[134:135], v[32:33], v[94:95], v[134:135]
	v_pk_add_f32 v[108:109], v[122:123], v[108:109]
	v_pk_add_f32 v[116:117], v[124:125], v[116:117]
	v_pk_add_f32 v[108:109], v[126:127], v[108:109]
	v_pk_add_f32 v[116:117], v[134:135], v[116:117]
	v_pk_mul_f32 v[122:123], v[108:109], v[108:109]
	v_pk_mul_f32 v[124:125], v[116:117], v[116:117]
	v_pk_fma_f32 v[122:123], v[122:123], s[26:27], v[128:129] op_sel_hi:[1,0,0] neg_lo:[1,0,0] neg_hi:[1,0,0]
	v_pk_fma_f32 v[124:125], v[124:125], s[26:27], v[128:129] op_sel_hi:[1,0,0] neg_lo:[1,0,0] neg_hi:[1,0,0]
	v_pk_mul_f32 v[122:123], v[108:109], v[122:123]
	v_pk_mul_f32 v[124:125], v[116:117], v[124:125]
	v_exp_f32_e32 v122, v122
	v_exp_f32_e32 v124, v124
	v_exp_f32_e32 v125, v125
	v_exp_f32_e32 v123, v123
	v_pk_mul_f32 v[126:127], v[30:31], v[114:115]
	v_pk_mul_f32 v[134:135], v[28:29], v[112:113]
	v_pk_add_f32 v[124:125], v[124:125], 1.0 op_sel_hi:[1,0]
	v_pk_add_f32 v[122:123], v[122:123], 1.0 op_sel_hi:[1,0]
	v_rcp_f32_e32 v124, v124
	v_rcp_f32_e32 v125, v125
	v_rcp_f32_e32 v122, v122
	v_rcp_f32_e32 v123, v123
	v_pk_mul_f32 v[116:117], v[116:117], v[124:125]
	v_pk_mul_f32 v[124:125], v[16:17], v[98:99]
	v_pk_mul_f32 v[108:109], v[108:109], v[122:123]
	s_nop 0
	v_lshlrev_b32_e32 v43, 16, v106
	v_and_b32_e32 v106, 0xffff0000, v106
	v_lshlrev_b32_e32 v122, 16, v107
	v_and_b32_e32 v107, 0xffff0000, v107
	v_mul_f32_e32 v106, v117, v106
	v_mul_f32_e32 v107, v109, v107
	v_mul_f32_e32 v43, v116, v43
	v_mul_f32_e32 v108, v108, v122
	v_cvt_pk_bf16_f32 v106, v43, v106
	v_cvt_pk_bf16_f32 v107, v108, v107
	flat_store_dwordx2 v[110:111], v[106:107] offset:2560
	s_nop 1
	v_mov_b64_e32 v[110:111], v[188:189]
	v_lshlrev_b32_e32 v106, 16, v104
	v_and_b32_e32 v107, 0xffff0000, v104
	v_lshlrev_b32_e32 v108, 16, v105
	v_and_b32_e32 v109, 0xffff0000, v105
	v_pk_mul_f32 v[104:105], v[6:7], v[92:93]
	v_pk_mul_f32 v[116:117], v[4:5], v[90:91]
	v_pk_mul_f32 v[122:123], v[18:19], v[102:103]
	v_pk_fma_f32 v[104:105], v[2:3], v[120:121], v[104:105]
	v_pk_fma_f32 v[116:117], v[0:1], v[118:119], v[116:117]
	v_pk_fma_f32 v[118:119], v[14:15], v[132:133], v[122:123]
	v_pk_fma_f32 v[104:105], v[10:11], v[88:89], v[104:105]
	v_pk_fma_f32 v[120:121], v[12:13], v[130:131], v[124:125]
	v_pk_fma_f32 v[122:123], v[26:27], v[140:141], v[126:127]
	v_pk_fma_f32 v[116:117], v[8:9], v[86:87], v[116:117]
	v_pk_fma_f32 v[118:119], v[22:23], v[96:97], v[118:119]
	v_pk_add_f32 v[104:105], v[38:39], v[104:105]
	v_pk_fma_f32 v[124:125], v[24:25], v[138:139], v[134:135]
	v_pk_fma_f32 v[120:121], v[20:21], v[94:95], v[120:121]
	v_pk_fma_f32 v[122:123], v[34:35], v[108:109], v[122:123]
	v_pk_add_f32 v[116:117], v[36:37], v[116:117]
	v_pk_add_f32 v[104:105], v[118:119], v[104:105]
	v_pk_fma_f32 v[124:125], v[32:33], v[106:107], v[124:125]
	v_pk_add_f32 v[116:117], v[120:121], v[116:117]
	v_pk_add_f32 v[104:105], v[122:123], v[104:105]
	v_pk_add_f32 v[116:117], v[124:125], v[116:117]
	v_pk_mul_f32 v[118:119], v[104:105], v[104:105]
	v_pk_mul_f32 v[120:121], v[116:117], v[116:117]
	v_pk_fma_f32 v[118:119], v[118:119], s[26:27], v[128:129] op_sel_hi:[1,0,0] neg_lo:[1,0,0] neg_hi:[1,0,0]
	v_pk_fma_f32 v[120:121], v[120:121], s[26:27], v[128:129] op_sel_hi:[1,0,0] neg_lo:[1,0,0] neg_hi:[1,0,0]
	v_pk_mul_f32 v[118:119], v[104:105], v[118:119]
	v_pk_mul_f32 v[120:121], v[116:117], v[120:121]
	v_exp_f32_e32 v118, v118
	v_exp_f32_e32 v119, v119
	v_exp_f32_e32 v120, v120
	v_exp_f32_e32 v121, v121
	v_pk_add_f32 v[118:119], v[118:119], 1.0 op_sel_hi:[1,0]
	v_pk_add_f32 v[120:121], v[120:121], 1.0 op_sel_hi:[1,0]
	v_rcp_f32_e32 v118, v118
	v_rcp_f32_e32 v119, v119
	v_rcp_f32_e32 v120, v120
	v_rcp_f32_e32 v121, v121
	v_pk_mul_f32 v[104:105], v[104:105], v[118:119]
	v_pk_mul_f32 v[116:117], v[116:117], v[120:121]
	s_nop 0
	v_lshlrev_b32_e32 v118, 16, v111
	v_and_b32_e32 v111, 0xffff0000, v111
	v_lshlrev_b32_e32 v43, 16, v110
	v_and_b32_e32 v110, 0xffff0000, v110
	v_mul_f32_e32 v105, v105, v111
	v_mul_f32_e32 v43, v116, v43
	v_mul_f32_e32 v110, v117, v110
	v_mul_f32_e32 v116, v104, v118
	v_cvt_pk_bf16_f32 v104, v43, v110
	v_cvt_pk_bf16_f32 v105, v116, v105
	flat_store_dwordx2 v[100:101], v[104:105] offset:2560
	s_waitcnt vmcnt(4)
	v_mov_b64_e32 v[148:149], v[158:159]
	v_mov_b64_e32 v[152:153], v[154:155]
	v_mov_b64_e32 v[150:151], v[156:157]
	v_mov_b64_e32 v[146:147], v[160:161]
	v_mov_b64_e32 v[124:125], v[162:163]
	v_mov_b64_e32 v[104:105], v[164:165]

.LBB0_959:
	s_or_b64 exec, exec, s[10:11]
	v_add_co_u32_e32 v130, vcc, s61, v128
	v_lshlrev_b32_e32 v142, 16, v118
	s_nop 0
	v_addc_co_u32_e32 v131, vcc, 0, v129, vcc
	v_lshl_add_u64 v[178:179], v[116:117], 0, s[88:89]
	v_lshl_add_u64 v[180:181], v[110:111], 0, s[88:89]
	v_lshl_add_u64 v[182:183], v[100:101], 0, s[88:89]
	s_cmp_eq_u32 s96, 0
	s_cbranch_scc1 .Lpf_A_st
	flat_load_dwordx2 v[138:139], v[130:131] offset:3584
	global_load_dwordx2 v[184:185], v[178:179], off offset:3584
	global_load_dwordx2 v[186:187], v[180:181], off offset:3584
	global_load_dwordx2 v[188:189], v[182:183], off offset:3584
	s_branch .Lpf_A_j
.Lpf_A_st:
	v_mov_b64_e32 v[138:139], v[190:191]
	v_mov_b64_e32 v[184:185], v[192:193]
	v_mov_b64_e32 v[186:187], v[194:195]
	v_mov_b64_e32 v[188:189], v[198:199]
.Lpf_A_j:
	v_lshl_add_u64 v[200:201], v[130:131], 0, s[84:85]
	v_lshl_add_u64 v[202:203], v[178:179], 0, s[84:85]
	v_lshl_add_u64 v[204:205], v[180:181], 0, s[84:85]
	v_lshl_add_u64 v[206:207], v[182:183], 0, s[84:85]
	global_load_dwordx2 v[190:191], v[200:201], off offset:3584
	global_load_dwordx2 v[192:193], v[202:203], off offset:3584
	global_load_dwordx2 v[194:195], v[204:205], off offset:3584
	global_load_dwordx2 v[198:199], v[206:207], off offset:3584
	v_and_b32_e32 v143, 0xffff0000, v118
	v_lshlrev_b32_e32 v144, 16, v119
	v_and_b32_e32 v145, 0xffff0000, v119
	v_pk_mul_f32 v[118:119], v[6:7], v[64:65]
	v_pk_mul_f32 v[156:157], v[4:5], v[62:63]
	v_pk_mul_f32 v[158:159], v[18:19], v[68:69]
	v_pk_fma_f32 v[118:119], v[2:3], v[76:77], v[118:119]
	v_lshlrev_b32_e32 v136, 16, v123
	v_and_b32_e32 v137, 0xffff0000, v123
	v_pk_mul_f32 v[160:161], v[16:17], v[66:67]
	v_pk_mul_f32 v[162:163], v[30:31], v[74:75]
	v_pk_fma_f32 v[156:157], v[0:1], v[72:73], v[156:157]
	v_pk_fma_f32 v[158:159], v[14:15], v[80:81], v[158:159]
	v_pk_fma_f32 v[118:119], v[10:11], v[144:145], v[118:119]
	v_lshlrev_b32_e32 v134, 16, v122
	v_and_b32_e32 v135, 0xffff0000, v122
	v_lshlrev_b32_e32 v122, 16, v126
	v_and_b32_e32 v123, 0xffff0000, v126
	v_lshlrev_b32_e32 v126, 16, v127
	v_and_b32_e32 v127, 0xffff0000, v127
	v_pk_mul_f32 v[164:165], v[28:29], v[70:71]
	v_pk_fma_f32 v[160:161], v[12:13], v[78:79], v[160:161]
	v_pk_fma_f32 v[162:163], v[26:27], v[84:85], v[162:163]
	v_pk_fma_f32 v[156:157], v[8:9], v[142:143], v[156:157]
	v_pk_fma_f32 v[158:159], v[22:23], v[136:137], v[158:159]
	v_pk_add_f32 v[118:119], v[38:39], v[118:119]
	v_pk_fma_f32 v[164:165], v[24:25], v[82:83], v[164:165]
	v_pk_fma_f32 v[160:161], v[20:21], v[134:135], v[160:161]
	v_pk_fma_f32 v[162:163], v[34:35], v[126:127], v[162:163]
	v_pk_add_f32 v[156:157], v[36:37], v[156:157]
	v_pk_add_f32 v[118:119], v[118:119], v[158:159]
	v_pk_fma_f32 v[164:165], v[32:33], v[122:123], v[164:165]
	v_pk_add_f32 v[156:157], v[156:157], v[160:161]
	v_pk_add_f32 v[118:119], v[118:119], v[162:163]
	v_mov_b64_e32 v[154:155], s[28:29]
	v_pk_add_f32 v[156:157], v[156:157], v[164:165]
	v_pk_mul_f32 v[158:159], v[118:119], v[118:119]
	v_pk_mul_f32 v[160:161], v[156:157], v[156:157]
	v_pk_fma_f32 v[158:159], v[158:159], s[26:27], v[154:155] op_sel_hi:[1,0,0] neg_lo:[1,0,0] neg_hi:[1,0,0]
	v_pk_fma_f32 v[160:161], v[160:161], s[26:27], v[154:155] op_sel_hi:[1,0,0] neg_lo:[1,0,0] neg_hi:[1,0,0]
	v_pk_mul_f32 v[158:159], v[118:119], v[158:159]
	v_pk_mul_f32 v[160:161], v[156:157], v[160:161]
	v_exp_f32_e32 v158, v158
	v_exp_f32_e32 v159, v159
	v_exp_f32_e32 v160, v160
	v_exp_f32_e32 v161, v161
	v_add_co_u32_e32 v162, vcc, s61, v116
	v_pk_add_f32 v[158:159], v[158:159], 1.0 op_sel_hi:[1,0]
	v_pk_add_f32 v[160:161], v[160:161], 1.0 op_sel_hi:[1,0]
	v_rcp_f32_e32 v158, v158
	v_rcp_f32_e32 v159, v159
	v_rcp_f32_e32 v160, v160
	v_rcp_f32_e32 v161, v161
	v_addc_co_u32_e32 v163, vcc, 0, v117, vcc
	v_pk_mul_f32 v[118:119], v[118:119], v[158:159]
	v_pk_mul_f32 v[156:157], v[156:157], v[160:161]
	v_pk_mul_f32 v[160:161], v[16:17], v[70:71]
	v_pk_mul_f32 v[164:165], v[30:31], v[88:89]
	v_pk_mul_f32 v[170:171], v[28:29], v[86:87]
	v_pk_fma_f32 v[160:161], v[12:13], v[82:83], v[160:161]
	v_pk_fma_f32 v[170:171], v[24:25], v[90:91], v[170:171]
	v_pk_fma_f32 v[164:165], v[26:27], v[92:93], v[164:165]
	v_pk_fma_f32 v[160:161], v[20:21], v[122:123], v[160:161]
	v_pk_mul_f32 v[172:173], v[28:29], v[94:95]
	v_pk_mul_f32 v[174:175], v[28:29], v[106:107]
	v_pk_fma_f32 v[172:173], v[24:25], v[98:99], v[172:173]
	v_pk_fma_f32 v[174:175], v[24:25], v[112:113], v[174:175]
	s_cmp_eq_u32 s96, 0
	s_cbranch_scc1 .Lpf_A_nw
	s_waitcnt vmcnt(0) lgkmcnt(0)
	s_mov_b32 s96, 0
.Lpf_A_nw:
	v_lshlrev_b32_e32 v158, 16, v139
	v_and_b32_e32 v139, 0xffff0000, v139
	v_lshlrev_b32_e32 v43, 16, v138
	v_and_b32_e32 v138, 0xffff0000, v138
	v_mul_f32_e32 v119, v119, v139
	v_mul_f32_e32 v43, v156, v43
	v_mul_f32_e32 v138, v157, v138
	v_mul_f32_e32 v156, v118, v158
	v_cvt_pk_bf16_f32 v118, v43, v138
	v_cvt_pk_bf16_f32 v119, v156, v119
	flat_store_dwordx2 v[130:131], v[118:119] offset:3584
	s_nop 1
	v_mov_b64_e32 v[130:131], v[184:185]
	v_pk_mul_f32 v[138:139], v[6:7], v[68:69]
	v_pk_mul_f32 v[156:157], v[4:5], v[66:67]
	v_pk_mul_f32 v[158:159], v[18:19], v[74:75]
	v_pk_fma_f32 v[156:157], v[0:1], v[78:79], v[156:157]
	v_pk_fma_f32 v[138:139], v[2:3], v[80:81], v[138:139]
	v_pk_fma_f32 v[158:159], v[14:15], v[84:85], v[158:159]
	v_pk_fma_f32 v[138:139], v[10:11], v[136:137], v[138:139]
	v_pk_fma_f32 v[156:157], v[8:9], v[134:135], v[156:157]
	v_lshlrev_b32_e32 v118, 16, v120
	v_and_b32_e32 v119, 0xffff0000, v120
	v_lshlrev_b32_e32 v120, 16, v121
	v_and_b32_e32 v121, 0xffff0000, v121
	v_pk_fma_f32 v[158:159], v[22:23], v[126:127], v[158:159]
	v_pk_add_f32 v[156:157], v[36:37], v[156:157]
	v_pk_add_f32 v[138:139], v[38:39], v[138:139]
	v_pk_fma_f32 v[164:165], v[34:35], v[120:121], v[164:165]
	v_pk_fma_f32 v[170:171], v[32:33], v[118:119], v[170:171]
	v_pk_add_f32 v[138:139], v[138:139], v[158:159]
	v_pk_add_f32 v[156:157], v[156:157], v[160:161]
	v_pk_add_f32 v[138:139], v[138:139], v[164:165]
	v_pk_add_f32 v[156:157], v[156:157], v[170:171]
	v_pk_mul_f32 v[158:159], v[138:139], v[138:139]
	v_pk_mul_f32 v[160:161], v[156:157], v[156:157]
	v_pk_fma_f32 v[158:159], v[158:159], s[26:27], v[154:155] op_sel_hi:[1,0,0] neg_lo:[1,0,0] neg_hi:[1,0,0]
	v_pk_fma_f32 v[160:161], v[160:161], s[26:27], v[154:155] op_sel_hi:[1,0,0] neg_lo:[1,0,0] neg_hi:[1,0,0]
	v_pk_mul_f32 v[158:159], v[138:139], v[158:159]
	v_pk_mul_f32 v[160:161], v[156:157], v[160:161]
	v_exp_f32_e32 v158, v158
	v_exp_f32_e32 v160, v160
	v_exp_f32_e32 v161, v161
	v_exp_f32_e32 v159, v159
	v_add_co_u32_e32 v164, vcc, s61, v110
	v_pk_add_f32 v[160:161], v[160:161], 1.0 op_sel_hi:[1,0]
	v_pk_add_f32 v[158:159], v[158:159], 1.0 op_sel_hi:[1,0]
	v_rcp_f32_e32 v160, v160
	v_rcp_f32_e32 v161, v161
	v_rcp_f32_e32 v158, v158
	v_rcp_f32_e32 v159, v159
	v_addc_co_u32_e32 v165, vcc, 0, v111, vcc
	v_pk_mul_f32 v[156:157], v[156:157], v[160:161]
	v_pk_mul_f32 v[138:139], v[138:139], v[158:159]
	v_pk_mul_f32 v[160:161], v[18:19], v[88:89]
	v_pk_mul_f32 v[170:171], v[30:31], v[96:97]
	v_pk_fma_f32 v[160:161], v[14:15], v[92:93], v[160:161]
	v_pk_fma_f32 v[170:171], v[26:27], v[102:103], v[170:171]
	v_pk_fma_f32 v[160:161], v[22:23], v[120:121], v[160:161]
	s_nop 0
	v_lshlrev_b32_e32 v43, 16, v130
	v_and_b32_e32 v130, 0xffff0000, v130
	v_lshlrev_b32_e32 v158, 16, v131
	v_and_b32_e32 v131, 0xffff0000, v131
	v_mul_f32_e32 v130, v157, v130
	v_mul_f32_e32 v131, v139, v131
	v_mul_f32_e32 v43, v156, v43
	v_mul_f32_e32 v138, v138, v158
	v_cvt_pk_bf16_f32 v130, v43, v130
	v_cvt_pk_bf16_f32 v131, v138, v131
	flat_store_dwordx2 v[162:163], v[130:131] offset:3584
	s_nop 1
	v_mov_b64_e32 v[138:139], v[186:187]
	v_pk_mul_f32 v[156:157], v[6:7], v[74:75]
	v_pk_mul_f32 v[158:159], v[4:5], v[70:71]
	v_pk_mul_f32 v[162:163], v[16:17], v[86:87]
	v_pk_fma_f32 v[158:159], v[0:1], v[82:83], v[158:159]
	v_pk_fma_f32 v[156:157], v[2:3], v[84:85], v[156:157]
	v_pk_fma_f32 v[162:163], v[12:13], v[90:91], v[162:163]
	v_pk_fma_f32 v[156:157], v[10:11], v[126:127], v[156:157]
	v_pk_fma_f32 v[158:159], v[8:9], v[122:123], v[158:159]
	v_lshlrev_b32_e32 v130, 16, v132
	v_and_b32_e32 v131, 0xffff0000, v132
	v_lshlrev_b32_e32 v132, 16, v133
	v_and_b32_e32 v133, 0xffff0000, v133
	v_pk_fma_f32 v[162:163], v[20:21], v[118:119], v[162:163]
	v_pk_add_f32 v[158:159], v[36:37], v[158:159]
	v_pk_add_f32 v[156:157], v[38:39], v[156:157]
	v_pk_fma_f32 v[170:171], v[34:35], v[132:133], v[170:171]
	v_pk_fma_f32 v[172:173], v[32:33], v[130:131], v[172:173]
	v_pk_add_f32 v[156:157], v[156:157], v[160:161]
	v_pk_add_f32 v[158:159], v[158:159], v[162:163]
	v_pk_add_f32 v[156:157], v[156:157], v[170:171]
	v_pk_add_f32 v[158:159], v[158:159], v[172:173]
	v_pk_mul_f32 v[160:161], v[156:157], v[156:157]
	v_pk_mul_f32 v[162:163], v[158:159], v[158:159]
	v_pk_fma_f32 v[160:161], v[160:161], s[26:27], v[154:155] op_sel_hi:[1,0,0] neg_lo:[1,0,0] neg_hi:[1,0,0]
	v_pk_fma_f32 v[162:163], v[162:163], s[26:27], v[154:155] op_sel_hi:[1,0,0] neg_lo:[1,0,0] neg_hi:[1,0,0]
	v_pk_mul_f32 v[160:161], v[156:157], v[160:161]
	v_pk_mul_f32 v[162:163], v[158:159], v[162:163]
	v_exp_f32_e32 v160, v160
	v_exp_f32_e32 v162, v162
	v_exp_f32_e32 v163, v163
	v_exp_f32_e32 v161, v161
	v_add_co_u32_e32 v170, vcc, s61, v100
	v_pk_add_f32 v[162:163], v[162:163], 1.0 op_sel_hi:[1,0]
	v_pk_add_f32 v[160:161], v[160:161], 1.0 op_sel_hi:[1,0]
	v_rcp_f32_e32 v162, v162
	v_rcp_f32_e32 v163, v163
	v_rcp_f32_e32 v160, v160
	v_rcp_f32_e32 v161, v161
	v_addc_co_u32_e32 v171, vcc, 0, v101, vcc
	v_pk_mul_f32 v[158:159], v[158:159], v[162:163]
	v_pk_mul_f32 v[156:157], v[156:157], v[160:161]
	v_pk_mul_f32 v[162:163], v[18:19], v[96:97]
	v_pk_mul_f32 v[172:173], v[30:31], v[108:109]
	v_pk_fma_f32 v[162:163], v[14:15], v[102:103], v[162:163]
	v_pk_fma_f32 v[172:173], v[26:27], v[114:115], v[172:173]
	v_pk_fma_f32 v[162:163], v[22:23], v[132:133], v[162:163]
	s_nop 0
	v_lshlrev_b32_e32 v43, 16, v138
	v_and_b32_e32 v138, 0xffff0000, v138
	v_lshlrev_b32_e32 v160, 16, v139
	v_and_b32_e32 v139, 0xffff0000, v139
	v_mul_f32_e32 v138, v159, v138
	v_mul_f32_e32 v139, v157, v139
	v_mul_f32_e32 v43, v158, v43
	v_mul_f32_e32 v156, v156, v160
	v_cvt_pk_bf16_f32 v138, v43, v138
	v_cvt_pk_bf16_f32 v139, v156, v139
	flat_store_dwordx2 v[164:165], v[138:139] offset:3584
	s_nop 1
	v_mov_b64_e32 v[156:157], v[188:189]
	v_pk_mul_f32 v[158:159], v[6:7], v[88:89]
	v_pk_mul_f32 v[160:161], v[4:5], v[86:87]
	v_pk_mul_f32 v[164:165], v[16:17], v[94:95]
	v_pk_fma_f32 v[160:161], v[0:1], v[90:91], v[160:161]
	v_pk_fma_f32 v[158:159], v[2:3], v[92:93], v[158:159]
	v_pk_fma_f32 v[164:165], v[12:13], v[98:99], v[164:165]
	v_pk_fma_f32 v[158:159], v[10:11], v[120:121], v[158:159]
	v_pk_fma_f32 v[160:161], v[8:9], v[118:119], v[160:161]
	v_lshlrev_b32_e32 v138, 16, v140
	v_and_b32_e32 v139, 0xffff0000, v140
	v_lshlrev_b32_e32 v140, 16, v141
	v_and_b32_e32 v141, 0xffff0000, v141
	v_pk_fma_f32 v[164:165], v[20:21], v[130:131], v[164:165]
	v_pk_add_f32 v[160:161], v[36:37], v[160:161]
	v_pk_add_f32 v[158:159], v[38:39], v[158:159]
	v_pk_fma_f32 v[172:173], v[34:35], v[140:141], v[172:173]
	v_pk_fma_f32 v[174:175], v[32:33], v[138:139], v[174:175]
	v_pk_add_f32 v[158:159], v[158:159], v[162:163]
	v_pk_add_f32 v[160:161], v[160:161], v[164:165]
	v_pk_add_f32 v[158:159], v[158:159], v[172:173]
	v_pk_add_f32 v[160:161], v[160:161], v[174:175]
	v_pk_mul_f32 v[162:163], v[158:159], v[158:159]
	v_pk_mul_f32 v[164:165], v[160:161], v[160:161]
	v_add_u32_e32 v43, 1, v168
	v_pk_fma_f32 v[164:165], v[164:165], s[26:27], v[154:155] op_sel_hi:[1,0,0] neg_lo:[1,0,0] neg_hi:[1,0,0]
	v_pk_fma_f32 v[154:155], v[162:163], s[26:27], v[154:155] op_sel_hi:[1,0,0] neg_lo:[1,0,0] neg_hi:[1,0,0]
	v_pk_mul_f32 v[162:163], v[160:161], v[164:165]
	v_pk_mul_f32 v[154:155], v[158:159], v[154:155]
	v_exp_f32_e32 v162, v162
	v_exp_f32_e32 v154, v154
	v_exp_f32_e32 v155, v155
	v_exp_f32_e32 v163, v163
	v_cmp_lt_u32_e32 vcc, v43, v53
	v_pk_add_f32 v[154:155], v[154:155], 1.0 op_sel_hi:[1,0]
	v_pk_add_f32 v[162:163], v[162:163], 1.0 op_sel_hi:[1,0]
	v_rcp_f32_e32 v154, v154
	v_rcp_f32_e32 v155, v155
	v_rcp_f32_e32 v162, v162
	v_rcp_f32_e32 v163, v163
	v_pk_mul_f32 v[154:155], v[158:159], v[154:155]
	v_pk_mul_f32 v[160:161], v[160:161], v[162:163]
	s_nop 0
	v_lshlrev_b32_e32 v159, 16, v157
	v_and_b32_e32 v157, 0xffff0000, v157
	v_lshlrev_b32_e32 v158, 16, v156
	v_and_b32_e32 v156, 0xffff0000, v156
	v_mul_f32_e32 v155, v155, v157
	v_mul_f32_e32 v158, v160, v158
	v_mul_f32_e32 v156, v161, v156
	v_mul_f32_e32 v159, v154, v159
	v_cvt_pk_bf16_f32 v154, v158, v156
	v_cvt_pk_bf16_f32 v155, v159, v155
	flat_store_dwordx2 v[170:171], v[154:155] offset:3584
	s_waitcnt vmcnt(4)
	s_and_saveexec_b64 s[36:37], vcc
	s_cbranch_execz .LBB0_969
	v_cmp_gt_u32_e64 s[10:11], 61, v168
	v_mov_b32_e32 v210, v42
	v_mov_b32_e32 v211, v42
	s_and_b64 s[4:5], s[6:7], s[10:11]
	v_mov_b64_e32 v[208:209], v[210:211]
	s_and_saveexec_b64 s[46:47], s[4:5]
	s_cbranch_execz .LBB0_962
	v_add_u32_e32 v43, s34, v52
	v_add_u32_e32 v72, 0xfffac200, v43
	v_mov_b32_e32 v73, v42
	v_lshl_add_u64 v[72:73], v[44:45], 0, v[72:73]
	flat_load_dwordx2 v[208:209], v[72:73]
.LBB0_962:
	s_or_b64 exec, exec, s[46:47]
	v_mov_b64_e32 v[212:213], v[210:211]
	s_and_saveexec_b64 s[46:47], s[10:11]
	s_cbranch_execz .LBB0_964
	v_add_co_u32_e32 v72, vcc, 0xd205000, v128
	s_nop 1
	v_addc_co_u32_e32 v73, vcc, 0, v129, vcc
	v_add_co_u32_e32 v76, vcc, 0xd205000, v116
	s_nop 1
	v_addc_co_u32_e32 v77, vcc, 0, v117, vcc
	flat_load_dwordx2 v[210:211], v[72:73]
	flat_load_dwordx2 v[212:213], v[76:77]

.LBB0_968:
	s_or_b64 exec, exec, s[10:11]
	v_add_co_u32_e32 v90, vcc, s62, v128
	v_pk_mul_f32 v[98:99], v[2:3], v[64:65]
	s_nop 0
	v_addc_co_u32_e32 v91, vcc, 0, v129, vcc
	v_lshl_add_u64 v[178:179], v[116:117], 0, s[90:91]
	v_lshl_add_u64 v[180:181], v[110:111], 0, s[90:91]
	v_lshl_add_u64 v[182:183], v[100:101], 0, s[90:91]
	v_mov_b64_e32 v[92:93], v[190:191]
	v_mov_b64_e32 v[184:185], v[192:193]
	v_mov_b64_e32 v[186:187], v[194:195]
	v_mov_b64_e32 v[188:189], v[198:199]
	v_lshl_add_u64 v[200:201], v[90:91], 0, s[84:85]
	v_lshl_add_u64 v[202:203], v[178:179], 0, s[84:85]
	v_lshl_add_u64 v[204:205], v[180:181], 0, s[84:85]
	v_lshl_add_u64 v[206:207], v[182:183], 0, s[84:85]
	global_load_dwordx2 v[190:191], v[200:201], off offset:1024
	global_load_dwordx2 v[192:193], v[202:203], off offset:-3072
	global_load_dwordx2 v[194:195], v[204:205], off offset:-3072
	global_load_dwordx2 v[198:199], v[206:207], off offset:-3072
	v_pk_mul_f32 v[102:103], v[0:1], v[62:63]
	v_lshlrev_b32_e32 v72, 16, v148
	v_and_b32_e32 v73, 0xffff0000, v148
	v_lshlrev_b32_e32 v76, 16, v149
	v_and_b32_e32 v77, 0xffff0000, v149
	v_pk_mul_f32 v[112:113], v[14:15], v[68:69]
	v_pk_mul_f32 v[114:115], v[12:13], v[66:67]
	v_pk_fma_f32 v[98:99], v[6:7], v[144:145], v[98:99]
	v_pk_fma_f32 v[102:103], v[4:5], v[142:143], v[102:103]
	v_lshlrev_b32_e32 v78, 16, v152
	v_and_b32_e32 v79, 0xffff0000, v152
	v_lshlrev_b32_e32 v80, 16, v153
	v_and_b32_e32 v81, 0xffff0000, v153
	v_pk_mul_f32 v[148:149], v[26:27], v[74:75]
	v_pk_mul_f32 v[152:153], v[24:25], v[70:71]
	v_pk_fma_f32 v[112:113], v[18:19], v[136:137], v[112:113]
	v_pk_fma_f32 v[114:115], v[16:17], v[134:135], v[114:115]
	v_pk_fma_f32 v[98:99], v[10:11], v[76:77], v[98:99]
	v_pk_fma_f32 v[102:103], v[8:9], v[72:73], v[102:103]
	v_lshlrev_b32_e32 v82, 16, v150
	v_and_b32_e32 v83, 0xffff0000, v150
	v_lshlrev_b32_e32 v84, 16, v151
	v_and_b32_e32 v85, 0xffff0000, v151
	v_pk_fma_f32 v[148:149], v[30:31], v[126:127], v[148:149]
	v_pk_fma_f32 v[152:153], v[28:29], v[122:123], v[152:153]
	v_pk_fma_f32 v[112:113], v[22:23], v[80:81], v[112:113]
	v_pk_fma_f32 v[114:115], v[20:21], v[78:79], v[114:115]
	v_pk_add_f32 v[98:99], v[38:39], v[98:99]
	v_pk_add_f32 v[102:103], v[36:37], v[102:103]
	v_pk_fma_f32 v[148:149], v[34:35], v[84:85], v[148:149]
	v_pk_fma_f32 v[152:153], v[32:33], v[82:83], v[152:153]
	v_pk_add_f32 v[98:99], v[98:99], v[112:113]
	v_pk_add_f32 v[102:103], v[102:103], v[114:115]
	v_pk_add_f32 v[98:99], v[98:99], v[148:149]
	v_pk_add_f32 v[102:103], v[102:103], v[152:153]
	v_mov_b64_e32 v[150:151], s[28:29]
	v_pk_mul_f32 v[112:113], v[98:99], v[98:99]
	v_pk_mul_f32 v[114:115], v[102:103], v[102:103]
	v_pk_fma_f32 v[112:113], v[112:113], s[26:27], v[150:151] op_sel_hi:[1,0,0] neg_lo:[1,0,0] neg_hi:[1,0,0]
	v_pk_fma_f32 v[114:115], v[114:115], s[26:27], v[150:151] op_sel_hi:[1,0,0] neg_lo:[1,0,0] neg_hi:[1,0,0]
	v_pk_mul_f32 v[112:113], v[98:99], v[112:113]
	v_pk_mul_f32 v[114:115], v[102:103], v[114:115]
	v_exp_f32_e32 v112, v112
	v_exp_f32_e32 v114, v114
	v_exp_f32_e32 v115, v115
	v_exp_f32_e32 v113, v113
	v_add_co_u32_e32 v148, vcc, s62, v116
	v_pk_add_f32 v[114:115], v[114:115], 1.0 op_sel_hi:[1,0]
	v_pk_add_f32 v[112:113], v[112:113], 1.0 op_sel_hi:[1,0]
	v_rcp_f32_e32 v114, v114
	v_rcp_f32_e32 v115, v115
	v_rcp_f32_e32 v112, v112
	v_rcp_f32_e32 v113, v113
	v_addc_co_u32_e32 v149, vcc, 0, v117, vcc
	v_pk_mul_f32 v[102:103], v[102:103], v[114:115]
	v_pk_mul_f32 v[98:99], v[98:99], v[112:113]
	v_pk_mul_f32 v[114:115], v[14:15], v[74:75]
	v_pk_mul_f32 v[152:153], v[26:27], v[88:89]
	v_pk_mul_f32 v[170:171], v[24:25], v[86:87]
	v_pk_fma_f32 v[114:115], v[18:19], v[126:127], v[114:115]
	v_pk_fma_f32 v[152:153], v[30:31], v[120:121], v[152:153]
	v_pk_fma_f32 v[170:171], v[28:29], v[118:119], v[170:171]
	v_pk_fma_f32 v[114:115], v[22:23], v[84:85], v[114:115]
	v_pk_mul_f32 v[172:173], v[24:25], v[94:95]
	v_pk_mul_f32 v[174:175], v[26:27], v[108:109]
	v_pk_fma_f32 v[172:173], v[28:29], v[130:131], v[172:173]
	v_pk_mul_f32 v[176:177], v[24:25], v[106:107]
	s_nop 0
	v_lshlrev_b32_e32 v43, 16, v92
	v_and_b32_e32 v92, 0xffff0000, v92
	v_lshlrev_b32_e32 v112, 16, v93
	v_and_b32_e32 v93, 0xffff0000, v93
	v_mul_f32_e32 v92, v103, v92
	v_mul_f32_e32 v93, v99, v93
	v_mul_f32_e32 v43, v102, v43
	v_mul_f32_e32 v98, v98, v112
	v_cvt_pk_bf16_f32 v92, v43, v92
	v_cvt_pk_bf16_f32 v93, v98, v93
	flat_store_dwordx2 v[90:91], v[92:93] offset:1024
	s_nop 1
	v_mov_b64_e32 v[98:99], v[184:185]
	v_pk_mul_f32 v[102:103], v[2:3], v[68:69]
	v_pk_mul_f32 v[112:113], v[0:1], v[66:67]
	v_lshlrev_b32_e32 v90, 16, v146
	v_and_b32_e32 v91, 0xffff0000, v146
	v_lshlrev_b32_e32 v92, 16, v147
	v_and_b32_e32 v93, 0xffff0000, v147
	v_pk_mul_f32 v[146:147], v[12:13], v[70:71]
	v_pk_fma_f32 v[102:103], v[6:7], v[136:137], v[102:103]
	v_pk_fma_f32 v[112:113], v[4:5], v[134:135], v[112:113]
	v_pk_fma_f32 v[146:147], v[16:17], v[122:123], v[146:147]
	v_pk_fma_f32 v[102:103], v[10:11], v[80:81], v[102:103]
	v_pk_fma_f32 v[112:113], v[8:9], v[78:79], v[112:113]
	v_pk_fma_f32 v[146:147], v[20:21], v[82:83], v[146:147]
	v_pk_add_f32 v[102:103], v[38:39], v[102:103]
	v_pk_add_f32 v[112:113], v[36:37], v[112:113]
	v_pk_fma_f32 v[152:153], v[34:35], v[92:93], v[152:153]
	v_pk_fma_f32 v[170:171], v[32:33], v[90:91], v[170:171]
	v_pk_add_f32 v[102:103], v[102:103], v[114:115]
	v_pk_add_f32 v[112:113], v[112:113], v[146:147]
	v_pk_add_f32 v[102:103], v[102:103], v[152:153]
	v_pk_add_f32 v[112:113], v[112:113], v[170:171]
	v_pk_mul_f32 v[114:115], v[102:103], v[102:103]
	v_pk_mul_f32 v[146:147], v[112:113], v[112:113]
	v_pk_fma_f32 v[114:115], v[114:115], s[26:27], v[150:151] op_sel_hi:[1,0,0] neg_lo:[1,0,0] neg_hi:[1,0,0]
	v_pk_fma_f32 v[146:147], v[146:147], s[26:27], v[150:151] op_sel_hi:[1,0,0] neg_lo:[1,0,0] neg_hi:[1,0,0]
	v_pk_mul_f32 v[114:115], v[102:103], v[114:115]
	v_pk_mul_f32 v[146:147], v[112:113], v[146:147]
	v_exp_f32_e32 v114, v114
	v_exp_f32_e32 v146, v146
	v_exp_f32_e32 v147, v147
	v_exp_f32_e32 v115, v115
	v_add_co_u32_e32 v152, vcc, s62, v110
	v_pk_add_f32 v[146:147], v[146:147], 1.0 op_sel_hi:[1,0]
	v_pk_add_f32 v[114:115], v[114:115], 1.0 op_sel_hi:[1,0]
	v_rcp_f32_e32 v146, v146
	v_rcp_f32_e32 v147, v147
	v_rcp_f32_e32 v114, v114
	v_rcp_f32_e32 v115, v115
	v_addc_co_u32_e32 v153, vcc, 0, v111, vcc
	v_pk_mul_f32 v[112:113], v[112:113], v[146:147]
	v_pk_mul_f32 v[102:103], v[102:103], v[114:115]
	v_pk_mul_f32 v[146:147], v[14:15], v[88:89]
	v_pk_mul_f32 v[170:171], v[26:27], v[96:97]
	v_pk_fma_f32 v[146:147], v[18:19], v[120:121], v[146:147]
	v_pk_fma_f32 v[170:171], v[30:31], v[132:133], v[170:171]
	v_pk_fma_f32 v[146:147], v[22:23], v[92:93], v[146:147]
	s_nop 0
	v_lshlrev_b32_e32 v43, 16, v98
	v_and_b32_e32 v98, 0xffff0000, v98
	v_lshlrev_b32_e32 v114, 16, v99
	v_and_b32_e32 v99, 0xffff0000, v99
	v_mul_f32_e32 v98, v113, v98
	v_mul_f32_e32 v99, v103, v99
	v_mul_f32_e32 v43, v112, v43
	v_mul_f32_e32 v102, v102, v114
	v_cvt_pk_bf16_f32 v98, v43, v98
	v_cvt_pk_bf16_f32 v99, v102, v99
	flat_store_dwordx2 v[148:149], v[98:99] offset:1024
	s_nop 1
	v_mov_b64_e32 v[112:113], v[186:187]
	v_lshlrev_b32_e32 v98, 16, v124
	v_and_b32_e32 v99, 0xffff0000, v124
	v_lshlrev_b32_e32 v102, 16, v125
	v_and_b32_e32 v103, 0xffff0000, v125
	v_pk_mul_f32 v[114:115], v[2:3], v[74:75]
	v_pk_mul_f32 v[124:125], v[0:1], v[70:71]
	v_pk_mul_f32 v[148:149], v[12:13], v[86:87]
	v_pk_fma_f32 v[114:115], v[6:7], v[126:127], v[114:115]
	v_pk_fma_f32 v[124:125], v[4:5], v[122:123], v[124:125]
	v_pk_fma_f32 v[148:149], v[16:17], v[118:119], v[148:149]
	v_pk_fma_f32 v[114:115], v[10:11], v[84:85], v[114:115]
	v_pk_fma_f32 v[124:125], v[8:9], v[82:83], v[124:125]
	v_pk_fma_f32 v[148:149], v[20:21], v[90:91], v[148:149]
	v_pk_add_f32 v[114:115], v[38:39], v[114:115]
	v_pk_add_f32 v[124:125], v[36:37], v[124:125]
	v_pk_fma_f32 v[170:171], v[34:35], v[102:103], v[170:171]
	v_pk_fma_f32 v[172:173], v[32:33], v[98:99], v[172:173]
	v_pk_add_f32 v[114:115], v[114:115], v[146:147]
	v_pk_add_f32 v[124:125], v[124:125], v[148:149]
	v_pk_add_f32 v[114:115], v[114:115], v[170:171]
	v_pk_add_f32 v[124:125], v[124:125], v[172:173]
	v_pk_mul_f32 v[146:147], v[114:115], v[114:115]
	v_pk_mul_f32 v[148:149], v[124:125], v[124:125]
	v_pk_fma_f32 v[146:147], v[146:147], s[26:27], v[150:151] op_sel_hi:[1,0,0] neg_lo:[1,0,0] neg_hi:[1,0,0]
	v_pk_fma_f32 v[148:149], v[148:149], s[26:27], v[150:151] op_sel_hi:[1,0,0] neg_lo:[1,0,0] neg_hi:[1,0,0]
	v_pk_mul_f32 v[146:147], v[114:115], v[146:147]
	v_pk_mul_f32 v[148:149], v[124:125], v[148:149]
	v_exp_f32_e32 v146, v146
	v_exp_f32_e32 v148, v148
	v_exp_f32_e32 v149, v149
	v_exp_f32_e32 v147, v147
	v_add_co_u32_e32 v170, vcc, s62, v100
	v_pk_add_f32 v[148:149], v[148:149], 1.0 op_sel_hi:[1,0]
	v_pk_add_f32 v[146:147], v[146:147], 1.0 op_sel_hi:[1,0]
	v_rcp_f32_e32 v148, v148
	v_rcp_f32_e32 v149, v149
	v_rcp_f32_e32 v146, v146
	v_rcp_f32_e32 v147, v147
	v_addc_co_u32_e32 v171, vcc, 0, v101, vcc
	v_pk_mul_f32 v[124:125], v[124:125], v[148:149]
	v_pk_mul_f32 v[114:115], v[114:115], v[146:147]
	v_pk_fma_f32 v[158:159], v[30:31], v[140:141], v[174:175]
	v_pk_fma_f32 v[174:175], v[28:29], v[138:139], v[176:177]
	s_nop 0
	v_lshlrev_b32_e32 v43, 16, v112
	v_and_b32_e32 v112, 0xffff0000, v112
	v_lshlrev_b32_e32 v146, 16, v113
	v_and_b32_e32 v113, 0xffff0000, v113
	v_mul_f32_e32 v112, v125, v112
	v_mul_f32_e32 v113, v115, v113
	v_mul_f32_e32 v43, v124, v43
	v_mul_f32_e32 v114, v114, v146
	v_cvt_pk_bf16_f32 v112, v43, v112
	v_cvt_pk_bf16_f32 v113, v114, v113
	flat_store_dwordx2 v[152:153], v[112:113] offset:1024
	s_nop 1
	v_mov_b64_e32 v[172:173], v[188:189]
	v_lshlrev_b32_e32 v112, 16, v104
	v_and_b32_e32 v113, 0xffff0000, v104
	v_lshlrev_b32_e32 v114, 16, v105
	v_and_b32_e32 v115, 0xffff0000, v105
	v_pk_mul_f32 v[104:105], v[2:3], v[88:89]
	v_pk_mul_f32 v[124:125], v[0:1], v[86:87]
	v_pk_mul_f32 v[146:147], v[14:15], v[96:97]
	v_pk_mul_f32 v[152:153], v[12:13], v[94:95]
	v_pk_fma_f32 v[104:105], v[6:7], v[120:121], v[104:105]
	v_pk_fma_f32 v[124:125], v[4:5], v[118:119], v[124:125]
	v_pk_fma_f32 v[146:147], v[18:19], v[132:133], v[146:147]
	v_pk_fma_f32 v[152:153], v[16:17], v[130:131], v[152:153]
	v_pk_fma_f32 v[104:105], v[10:11], v[92:93], v[104:105]
	v_pk_fma_f32 v[124:125], v[8:9], v[90:91], v[124:125]
	v_pk_fma_f32 v[146:147], v[22:23], v[102:103], v[146:147]
	v_pk_fma_f32 v[152:153], v[20:21], v[98:99], v[152:153]
	v_pk_add_f32 v[104:105], v[38:39], v[104:105]
	v_pk_add_f32 v[124:125], v[36:37], v[124:125]
	v_pk_fma_f32 v[158:159], v[34:35], v[114:115], v[158:159]
	v_pk_fma_f32 v[174:175], v[32:33], v[112:113], v[174:175]
	v_pk_add_f32 v[104:105], v[104:105], v[146:147]
	v_pk_add_f32 v[124:125], v[124:125], v[152:153]
	v_pk_add_f32 v[104:105], v[104:105], v[158:159]
	v_pk_add_f32 v[158:159], v[124:125], v[174:175]
	v_pk_mul_f32 v[124:125], v[104:105], v[104:105]
	v_pk_mul_f32 v[146:147], v[158:159], v[158:159]
	v_pk_fma_f32 v[124:125], v[124:125], s[26:27], v[150:151] op_sel_hi:[1,0,0] neg_lo:[1,0,0] neg_hi:[1,0,0]
	v_pk_fma_f32 v[146:147], v[146:147], s[26:27], v[150:151] op_sel_hi:[1,0,0] neg_lo:[1,0,0] neg_hi:[1,0,0]
	v_pk_mul_f32 v[124:125], v[104:105], v[124:125]
	v_pk_mul_f32 v[146:147], v[158:159], v[146:147]
	v_exp_f32_e32 v124, v124
	v_exp_f32_e32 v146, v146
	v_exp_f32_e32 v147, v147
	v_exp_f32_e32 v125, v125
	v_pk_add_f32 v[146:147], v[146:147], 1.0 op_sel_hi:[1,0]
	v_pk_add_f32 v[124:125], v[124:125], 1.0 op_sel_hi:[1,0]
	v_rcp_f32_e32 v154, v146
	v_rcp_f32_e32 v155, v147
	v_rcp_f32_e32 v156, v124
	v_rcp_f32_e32 v157, v125
	v_pk_mul_f32 v[154:155], v[158:159], v[154:155]
	v_pk_mul_f32 v[104:105], v[104:105], v[156:157]
	s_nop 0
	v_and_b32_e32 v158, 0xffff0000, v173
	v_lshlrev_b32_e32 v43, 16, v172
	v_and_b32_e32 v156, 0xffff0000, v172
	v_lshlrev_b32_e32 v157, 16, v173
	v_mul_f32_e32 v105, v105, v158
	v_mul_f32_e32 v43, v154, v43
	v_mul_f32_e32 v154, v155, v156
	v_mul_f32_e32 v155, v104, v157
	v_cvt_pk_bf16_f32 v104, v43, v154
	v_cvt_pk_bf16_f32 v105, v155, v105
	flat_store_dwordx2 v[170:171], v[104:105] offset:1024
	s_waitcnt vmcnt(4)
	v_mov_b64_e32 v[148:149], v[208:209]
	v_mov_b64_e32 v[152:153], v[210:211]
	v_mov_b64_e32 v[150:151], v[212:213]
	v_mov_b64_e32 v[146:147], v[160:161]
	v_mov_b64_e32 v[124:125], v[162:163]
	v_mov_b64_e32 v[104:105], v[164:165]
